# GLA chunk-state phase: its two half-workgroups (separate units, separate LDS halves) run one barrier apart (waves 4-7 take one extra barrier on entry, waves 0-3 one on exit)
# speedup vs baseline: 1.0026x; 1.0026x over previous
.Lswap_ga_entry:
	v_readfirstlane_b32 s32, v208
	s_cmp_lt_u32 s32, 0x100
	s_cbranch_scc1 .Lga_stag_a
	s_barrier

.Lswap_ga_exit:
	v_readfirstlane_b32 s32, v208
	s_cmp_ge_u32 s32, 0x100
	s_cbranch_scc1 .Lga_stag_b
	s_barrier
